# plus S5 BtG table fill: one state-power load and four 16-byte input-matrix loads per output instead of eight serialized load rounds
# baseline (speedup 1.0000x reference)
; DEVI unsigned cvt_pk(float lo, float hi) { f32v2_t f = {lo, hi}; bf16v2_t v = __builtin_convertvector(f, bf16v2_t); return __builtin_bit_cast(unsigned, v); }
; DEVI void s5_fill(const Params& p) {
;     ...
;     for (int e = gt; e < 64 * 256 * 64; e += nthr) { const int k8 = (e & 63) * 8, n = (e >> 6) & 255, g = e >> 14, s = k8 >> 4, h0 = k8 & 15; float v[8];
; #pragma unroll
;         for (int j = 0; j < 8; ++j) { float x = 0.f; if (n < 128) { const int pp = n & 63; const size_t gp = (size_t)g * 64 + pp; const float ar = apow[(gp * 34 + 31 - s) * 2], ai = apow[(gp * 34 + 31 - s) * 2 + 1];
;                 const float br = bb[(gp * 16 + h0 + j) * 2], bi = bb[(gp * 16 + h0 + j) * 2 + 1]; x = (n < 64) ? (ar * br - ai * bi) : (ar * bi + ai * br); } v[j] = x; }
;         u32x4 w; w.x = cvt_pk(v[0], v[1]); w.y = cvt_pk(v[2], v[3]); w.z = cvt_pk(v[4], v[5]); w.w = cvt_pk(v[6], v[7]);
;         *(u32x4*)(btg + ((size_t)g * 256 + n) * 512 + k8) = w; }
.LBB0_1054:
	v_ashrrev_i32_e32 v0, 14, v19
	s_waitcnt lgkmcnt(0)
	v_ashrrev_i32_e32 v1, 31, v0
	v_lshrrev_b32_e32 v2, 6, v19
	v_lshlrev_b64 v[4:5], 6, v[0:1]
	v_bfe_u32 v7, v19, 6, 8
	v_bfe_u32 v8, v6, 4, 5
	s_movk_i32 s0, 0x80
	v_and_or_b32 v4, v2, 63, v4
	v_cmp_gt_u32_e32 vcc, s0, v7
	v_mul_hi_i32_i24_e32 v3, 34, v4
	v_mul_i32_i24_e32 v2, 34, v4
	v_xor_b32_e32 v8, 31, v8
	v_lshlrev_b64 v[4:5], 4, v[4:5]
	v_readlane_b32 s0, v252, 32
	v_lshl_add_u64 v[2:3], v[2:3], 0, v[8:9]
	v_and_or_b32 v4, v6, 8, v4
	v_readlane_b32 s1, v252, 33
	v_lshl_add_u64 v[2:3], v[2:3], 3, s[56:57]
	v_cmp_gt_u32_e64 s[2:3], 64, v7
	v_mov_b32_e32 v8, 0
	v_lshl_add_u64 v[4:5], v[4:5], 3, s[0:1]
	v_mov_b32_e32 v10, 0
	v_mov_b32_e32 v10, 0
	v_mov_b32_e32 v8, 0
	v_mov_b32_e32 v12, 0
	v_mov_b32_e32 v11, 0
	v_mov_b32_e32 v14, 0
	v_mov_b32_e32 v13, 0
	v_mov_b32_e32 v16, 0
	v_mov_b32_e32 v15, 0
	s_and_saveexec_b64 s[8:9], vcc
	s_cbranch_execz .LBB0_1053
	global_load_dwordx2 v[2:3], v[2:3], off
	global_load_dwordx4 v[24:27], v[4:5], off
	global_load_dwordx4 v[28:31], v[4:5], off offset:16
	global_load_dwordx4 v[32:35], v[4:5], off offset:32
	global_load_dwordx4 v[36:39], v[4:5], off offset:48
	s_waitcnt vmcnt(0)
	v_pk_mul_f32 v[20:21], v[2:3], v[24:25]
	v_pk_mul_f32 v[22:23], v[2:3], v[24:25] op_sel:[1,0] op_sel_hi:[0,1]
	v_sub_f32_e32 v20, v20, v21
	v_add_f32_e32 v22, v22, v23
	v_cndmask_b32_e64 v10, v22, v20, s[2:3]
	v_pk_mul_f32 v[20:21], v[2:3], v[26:27]
	v_pk_mul_f32 v[22:23], v[2:3], v[26:27] op_sel:[1,0] op_sel_hi:[0,1]
	v_sub_f32_e32 v20, v20, v21
	v_add_f32_e32 v22, v22, v23
	v_cndmask_b32_e64 v8, v22, v20, s[2:3]
	v_pk_mul_f32 v[20:21], v[2:3], v[28:29]
	v_pk_mul_f32 v[22:23], v[2:3], v[28:29] op_sel:[1,0] op_sel_hi:[0,1]
	v_sub_f32_e32 v20, v20, v21
	v_add_f32_e32 v22, v22, v23
	v_cndmask_b32_e64 v12, v22, v20, s[2:3]
	v_pk_mul_f32 v[20:21], v[2:3], v[30:31]
	v_pk_mul_f32 v[22:23], v[2:3], v[30:31] op_sel:[1,0] op_sel_hi:[0,1]
	v_sub_f32_e32 v20, v20, v21
	v_add_f32_e32 v22, v22, v23
	v_cndmask_b32_e64 v11, v22, v20, s[2:3]
	v_pk_mul_f32 v[20:21], v[2:3], v[32:33]
	v_pk_mul_f32 v[22:23], v[2:3], v[32:33] op_sel:[1,0] op_sel_hi:[0,1]
	v_sub_f32_e32 v20, v20, v21
	v_add_f32_e32 v22, v22, v23
	v_cndmask_b32_e64 v14, v22, v20, s[2:3]
	v_pk_mul_f32 v[20:21], v[2:3], v[34:35]
	v_pk_mul_f32 v[22:23], v[2:3], v[34:35] op_sel:[1,0] op_sel_hi:[0,1]
	v_sub_f32_e32 v20, v20, v21
	v_add_f32_e32 v22, v22, v23
	v_cndmask_b32_e64 v13, v22, v20, s[2:3]
	v_pk_mul_f32 v[20:21], v[2:3], v[36:37]
	v_pk_mul_f32 v[22:23], v[2:3], v[36:37] op_sel:[1,0] op_sel_hi:[0,1]
	v_sub_f32_e32 v20, v20, v21
	v_add_f32_e32 v22, v22, v23
	v_cndmask_b32_e64 v16, v22, v20, s[2:3]
	v_pk_mul_f32 v[20:21], v[2:3], v[38:39]
	v_pk_mul_f32 v[22:23], v[2:3], v[38:39] op_sel:[1,0] op_sel_hi:[0,1]
	v_sub_f32_e32 v20, v20, v21
	v_add_f32_e32 v22, v22, v23
	v_cndmask_b32_e64 v15, v22, v20, s[2:3]
	s_branch .LBB0_1053
